# layer-1 in-projection: tail fp6 units dealt three each to the 96 workgroups with only two bf16 units (balance), on top of the software-pipelined fp6 loop
# speedup vs baseline: 1.0105x; 1.0105x over previous
.LBB0_968:
	v_readlane_b32 s2, v249, 34
	s_add_i32 s71, s70, 1
	v_readlane_b32 s3, v249, 35
	s_mul_hi_i32 s3, s71, s2
	s_mul_i32 s2, s71, s2
	s_add_u32 s2, s2, s25
	s_addc_u32 s3, s3, s36
	v_readlane_b32 s79, v249, 34
	s_cmp_lt_u32 s71, 9
	s_cbranch_scc1 .Lrb_keep_L1
	s_cmp_lg_u32 s79, 0x100
	s_cbranch_scc1 .Lrb_keep_L1
	s_mov_b32 s2, 0x7fffffff
	s_mov_b32 s3, 0
	s_cmp_lt_u32 s76, 0xa0
	s_cbranch_scc1 .Lrb_keep_L1
	s_cmp_gt_u32 s71, 11
	s_cbranch_scc1 .Lrb_keep_L1
	s_sub_u32 s79, s76, 0xa0
	s_lshr_b32 s79, s79, 3
	s_mul_i32 s79, s79, 3
	s_sub_u32 s80, s71, 9
	s_add_u32 s79, s79, s80
	s_lshl_b32 s79, s79, 3
	s_and_b32 s80, s76, 7
	s_add_u32 s79, s79, s80
	s_add_u32 s2, s79, 0x900
.Lrb_keep_L1:
	v_cmp_gt_i64_e64 s[10:11], s[2:3], v[188:189]
	v_cmp_lt_i64_e64 s[14:15], s[2:3], v[186:187]
	s_and_b64 vcc, exec, s[10:11]
	s_cbranch_vccnz .LBB0_970
	s_ashr_i32 s3, s2, 31
	s_lshr_b32 s3, s3, 29
	s_add_i32 s3, s2, s3
	s_ashr_i32 s12, s3, 3
	s_and_b32 s3, s3, -8
	s_sub_i32 s2, s2, s3
	s_cmp_lt_i32 s2, 0
	s_movk_i32 s3, 0x145
	s_cselect_b32 s3, s3, 0x144
	s_mul_i32 s2, s3, s2
	s_add_i32 s2, s2, s12
	s_mul_hi_i32 s3, s2, 0x1948b0fd
	s_lshr_b32 s12, s3, 31
	s_ashr_i32 s3, s3, 6
	s_add_i32 s3, s3, s12
	s_lshl_b32 s12, s3, 3
	s_sub_i32 s13, 32, s12
	s_min_i32 s13, s13, 8
	s_abs_i32 s26, s13
	v_cvt_f32_u32_e32 v2, s26
	s_sub_i32 s28, 0, s26
	s_mulk_i32 s3, 0x288
	s_sub_i32 s2, s2, s3
	v_rcp_iflag_f32_e32 v2, v2
	s_abs_i32 s3, s2
	s_xor_b32 s27, s2, s13
	s_ashr_i32 s27, s27, 31
	v_mul_f32_e32 v2, 0x4f7ffffe, v2
	v_cvt_u32_f32_e32 v2, v2
	s_nop 0
	v_readfirstlane_b32 s29, v2
	s_mul_i32 s28, s28, s29
	s_mul_hi_u32 s28, s29, s28
	s_add_i32 s29, s29, s28
	s_mul_hi_u32 s28, s3, s29
	s_mul_i32 s29, s28, s26
	s_sub_i32 s3, s3, s29
	s_add_i32 s30, s28, 1
	s_sub_i32 s29, s3, s26
	s_cmp_ge_u32 s3, s26
	s_cselect_b32 s28, s30, s28
	s_cselect_b32 s3, s29, s3
	s_add_i32 s29, s28, 1
	s_cmp_ge_u32 s3, s26
	s_cselect_b32 s3, s29, s28
	s_xor_b32 s3, s3, s27
	s_sub_i32 s68, s3, s27
	s_mul_i32 s3, s68, s13
	s_sub_i32 s2, s2, s3
	s_add_i32 s69, s2, s12
